# v82 plus the small de-serialisations stacked: differential-mixer unit epilogue loads, q/kv epilogue sum-of-squares loads, rewritten modulation-table inner loop
# baseline (speedup 1.0000x reference)
.LBB0_638:
	v_mov_b32_e32 v64, v185
	s_lshl_b32 s0, s20, 8
	v_mbcnt_lo_u32_b32 v64, -1, v64
	v_readlane_b32 s1, v253, 63
	v_mbcnt_hi_u32_b32 v64, -1, v64
	s_add_i32 s0, s0, s1
	v_and_or_b32 v176, v64, 15, s0
	s_cmpk_lt_i32 s20, 0x80
	s_cselect_b64 s[42:43], -1, 0
	v_ashrrev_i32_e32 v177, 31, v176
	s_lshl_b32 s0, s2, 8
	v_ashrrev_i32_e32 v64, 1, v64
	v_readlane_b32 s1, v254, 1
	v_and_b32_e32 v64, -8, v64
	s_or_b32 s0, s0, s1
	v_lshl_add_u64 v[180:181], v[176:177], 2, s[12:13]
	v_add_u32_e32 v178, s0, v64
	global_load_dword v64, v[180:181], off
	global_load_dword v65, v[180:181], off offset:64
	global_load_dword v66, v[180:181], off offset:128
	global_load_dword v132, v[180:181], off offset:192
	global_load_dword v220, v[180:181], off offset:512
	global_load_dword v221, v[180:181], off offset:576
	global_load_dword v222, v[180:181], off offset:640
	global_load_dword v223, v[180:181], off offset:704
	s_mov_b32 s2, 0xf800000
	s_mov_b32 s3, 0x3e16c740
	v_lshlrev_b32_e32 v193, 4, v176
	v_and_b32_e32 v196, 0x7cf0, v193
	s_waitcnt vmcnt(0)
	v_fmamk_f32 v64, v64, 0x3baaaaab, v245
	v_cmp_gt_f32_e32 vcc, s2, v64
	v_mul_f32_e32 v67, 0x4f800000, v64
	s_nop 0
	v_cndmask_b32_e32 v64, v64, v67, vcc
	v_sqrt_f32_e32 v133, v64
	v_mov_b32_e32 v67, 0
	v_mov_b32_e32 v147, v67
	v_mov_b32_e32 v146, v67
	v_add_u32_e32 v134, -1, v133
	v_fma_f32 v135, -v134, v133, v64
	v_cmp_ge_f32_e64 s[0:1], 0, v135
	v_add_u32_e32 v135, 1, v133
	v_mov_b32_e32 v145, v67
	v_cndmask_b32_e64 v134, v133, v134, s[0:1]
	v_fma_f32 v133, -v135, v133, v64
	v_cmp_lt_f32_e64 s[0:1], 0, v133
	v_mov_b32_e32 v144, v67
	v_mov_b32_e32 v155, v67
	v_cndmask_b32_e64 v133, v134, v135, s[0:1]
	v_mul_f32_e32 v134, 0x37800000, v133
	v_cndmask_b32_e32 v133, v133, v134, vcc
	v_cmp_class_f32_e32 vcc, v64, v250
	v_mov_b32_e32 v154, v67
	v_mov_b32_e32 v153, v67
	v_cndmask_b32_e32 v64, v133, v64, vcc
	v_div_scale_f32 v133, s[0:1], v64, v64, s3
	v_rcp_f32_e32 v134, v133
	v_mov_b32_e32 v152, v67
	v_fma_f32 v135, -v133, v134, 1.0
	v_fmac_f32_e32 v134, v135, v134
	v_div_scale_f32 v135, vcc, s3, v64, s3
	v_mul_f32_e32 v136, v135, v134
	v_fma_f32 v137, -v133, v136, v135
	v_fmac_f32_e32 v136, v137, v134
	v_fma_f32 v133, -v133, v136, v135
	v_div_fmas_f32 v133, v133, v134, v136
	v_div_fixup_f32 v182, v133, v64, s3
	v_fmamk_f32 v64, v65, 0x3baaaaab, v245
	v_cmp_gt_f32_e32 vcc, s2, v64
	v_mul_f32_e32 v65, 0x4f800000, v64
	s_nop 0
	v_cndmask_b32_e32 v64, v64, v65, vcc
	v_sqrt_f32_e32 v65, v64
	s_nop 0
	v_add_u32_e32 v133, -1, v65
	v_fma_f32 v134, -v133, v65, v64
	v_cmp_ge_f32_e64 s[0:1], 0, v134
	v_add_u32_e32 v134, 1, v65
	s_nop 0
	v_cndmask_b32_e64 v133, v65, v133, s[0:1]
	v_fma_f32 v65, -v134, v65, v64
	v_cmp_lt_f32_e64 s[0:1], 0, v65
	s_nop 1
	v_cndmask_b32_e64 v65, v133, v134, s[0:1]
	v_mul_f32_e32 v133, 0x37800000, v65
	v_cndmask_b32_e32 v65, v65, v133, vcc
	v_cmp_class_f32_e32 vcc, v64, v250
	s_nop 1
	v_cndmask_b32_e32 v64, v65, v64, vcc
	v_div_scale_f32 v65, s[0:1], v64, v64, s3
	v_rcp_f32_e32 v133, v65
	s_nop 0
	v_fma_f32 v134, -v65, v133, 1.0
	v_fmac_f32_e32 v133, v134, v133
	v_div_scale_f32 v134, vcc, s3, v64, s3
	v_mul_f32_e32 v135, v134, v133
	v_fma_f32 v136, -v65, v135, v134
	v_fmac_f32_e32 v135, v136, v133
	v_fma_f32 v65, -v65, v135, v134
	v_div_fmas_f32 v65, v65, v133, v135
	v_div_fixup_f32 v190, v65, v64, s3
	v_fmamk_f32 v64, v66, 0x3baaaaab, v245
	v_cmp_gt_f32_e32 vcc, s2, v64
	v_mul_f32_e32 v65, 0x4f800000, v64
	s_nop 0
	v_cndmask_b32_e32 v64, v64, v65, vcc
	v_sqrt_f32_e32 v65, v64
	s_nop 0
	v_add_u32_e32 v66, -1, v65
	v_fma_f32 v133, -v66, v65, v64
	v_cmp_ge_f32_e64 s[0:1], 0, v133
	v_add_u32_e32 v133, 1, v65
	s_nop 0
	v_cndmask_b32_e64 v66, v65, v66, s[0:1]
	v_fma_f32 v65, -v133, v65, v64
	v_cmp_lt_f32_e64 s[0:1], 0, v65
	s_nop 1
	v_cndmask_b32_e64 v65, v66, v133, s[0:1]
	v_mul_f32_e32 v66, 0x37800000, v65
	v_cndmask_b32_e32 v65, v65, v66, vcc
	v_cmp_class_f32_e32 vcc, v64, v250
	s_nop 1
	v_cndmask_b32_e32 v64, v65, v64, vcc
	v_div_scale_f32 v65, s[0:1], v64, v64, s3
	v_rcp_f32_e32 v66, v65
	s_nop 0
	v_fma_f32 v133, -v65, v66, 1.0
	v_fmac_f32_e32 v66, v133, v66
	v_div_scale_f32 v133, vcc, s3, v64, s3
	v_mul_f32_e32 v134, v133, v66
	v_fma_f32 v135, -v65, v134, v133
	v_fmac_f32_e32 v134, v135, v66
	v_fma_f32 v65, -v65, v134, v133
	v_div_fmas_f32 v65, v65, v66, v134
	v_div_fixup_f32 v192, v65, v64, s3
	v_fmamk_f32 v64, v132, 0x3baaaaab, v245
	v_cmp_gt_f32_e32 vcc, s2, v64
	v_mul_f32_e32 v65, 0x4f800000, v64
	s_mov_b32 s2, 0x2aaaaaab
	v_cndmask_b32_e32 v64, v64, v65, vcc
	v_sqrt_f32_e32 v65, v64
	v_mov_b32_e32 v135, v67
	v_add_u32_e32 v66, -1, v65
	v_fma_f32 v132, -v66, v65, v64
	v_cmp_ge_f32_e64 s[0:1], 0, v132
	v_add_u32_e32 v132, 1, v65
	s_nop 0
	v_cndmask_b32_e64 v66, v65, v66, s[0:1]
	v_fma_f32 v65, -v132, v65, v64
	v_cmp_lt_f32_e64 s[0:1], 0, v65
	s_nop 1
	v_cndmask_b32_e64 v65, v66, v132, s[0:1]
	v_mul_f32_e32 v66, 0x37800000, v65
	v_cndmask_b32_e32 v65, v65, v66, vcc
	v_cmp_class_f32_e32 vcc, v64, v250
	s_nop 1
	v_cndmask_b32_e32 v64, v65, v64, vcc
	v_div_scale_f32 v65, s[0:1], v64, v64, s3
	v_rcp_f32_e32 v66, v65
	s_movk_i32 s0, 0x180
	v_cmp_gt_i32_e64 s[0:1], s0, v178
	v_fma_f32 v132, -v65, v66, 1.0
	v_fmac_f32_e32 v66, v132, v66
	v_div_scale_f32 v132, vcc, s3, v64, s3
	v_mul_f32_e32 v133, v132, v66
	v_fma_f32 v134, -v65, v133, v132
	v_fmac_f32_e32 v133, v134, v66
	v_fma_f32 v65, -v65, v133, v132
	v_div_fmas_f32 v65, v65, v66, v133
	v_div_fixup_f32 v194, v65, v64, s3
	v_mul_hi_i32 v64, v178, s2
	v_lshrrev_b32_e32 v177, 31, v64
	v_lshrrev_b32_e32 v195, 4, v64
	v_mov_b32_e32 v66, v67
	v_mov_b32_e32 v65, v67
	v_mov_b32_e32 v64, v67
	v_mov_b32_e32 v134, v67
	v_mov_b32_e32 v133, v67
	v_mov_b32_e32 v132, v67
	s_and_saveexec_b64 s[2:3], s[0:1]
	s_cbranch_execz .LBB0_642
	v_add_u32_e32 v64, v195, v177
	s_movk_i32 s4, 0x60
	v_mul_lo_u32 v64, v64, s4
	v_sub_u32_e32 v179, v178, v64
	v_cmp_lt_i32_e32 vcc, 63, v179
	s_and_b64 vcc, s[42:43], vcc
	v_mov_b32_e32 v160, 0
	v_mov_b32_e32 v161, 0
	v_mov_b32_e32 v162, 0
	v_mov_b32_e32 v163, 0
	v_mov_b32_e32 v152, 0
	v_mov_b32_e32 v153, 0
	v_mov_b32_e32 v154, 0
	v_mov_b32_e32 v155, 0
	v_mov_b32_e32 v144, 0
	v_mov_b32_e32 v145, 0
	v_mov_b32_e32 v146, 0
	v_mov_b32_e32 v147, 0
	v_mov_b32_e32 v132, 0
	v_mov_b32_e32 v133, 0
	v_mov_b32_e32 v134, 0
	v_mov_b32_e32 v135, 0
	v_mov_b32_e32 v64, 0
	v_mov_b32_e32 v65, 0
	v_mov_b32_e32 v66, 0
	v_mov_b32_e32 v67, 0
	s_and_saveexec_b64 s[4:5], vcc
	s_cbranch_execz .LBB0_641
	v_subrev_u32_e32 v64, 64, v179
	v_lshrrev_b32_e32 v184, 1, v64
	v_lshlrev_b64 v[64:65], 2, v[184:185]
	v_lshl_add_u64 v[66:67], s[8:9], 0, v[64:65]
	v_lshlrev_b32_e32 v184, 2, v196
	v_lshl_add_u64 v[64:65], s[10:11], 0, v[64:65]
	v_lshl_add_u64 v[66:67], v[66:67], 0, v[184:185]
	v_lshl_add_u64 v[64:65], v[64:65], 0, v[184:185]
	global_load_dwordx4 v[152:155], v[66:67], off
	global_load_dwordx4 v[144:147], v[66:67], off offset:1024
	global_load_dwordx4 v[132:135], v[66:67], off offset:2048
	global_load_dwordx4 v[160:163], v[66:67], off offset:3072
	global_load_dwordx4 v[156:159], v[64:65], off
	global_load_dwordx4 v[148:151], v[64:65], off offset:1024
	global_load_dwordx4 v[136:139], v[64:65], off offset:2048
	global_load_dwordx4 v[140:143], v[64:65], off offset:3072
	s_waitcnt vmcnt(0)
	v_mov_b32_e32 v64, v160
	v_mov_b32_e32 v65, v161
	v_mov_b32_e32 v66, v162
	v_mov_b32_e32 v67, v163

.LBB0_646:
	s_or_b64 exec, exec, s[4:5]
	s_nop 1
	v_mov_b32_e32 v68, v220
	v_mov_b32_e32 v69, v221
	v_mov_b32_e32 v71, v222
	v_mov_b32_e32 v73, v223
	s_mov_b32 s19, 0xf800000
	s_mov_b32 s20, 0x3e16c740
	v_fmamk_f32 v68, v68, 0x3baaaaab, v245
	v_cmp_gt_f32_e32 vcc, s19, v68
	v_mul_f32_e32 v70, 0x4f800000, v68
	v_fmamk_f32 v69, v69, 0x3baaaaab, v245
	v_cndmask_b32_e32 v68, v68, v70, vcc
	v_sqrt_f32_e32 v70, v68
	s_nop 0
	v_add_u32_e32 v72, -1, v70
	v_fma_f32 v74, -v72, v70, v68
	v_cmp_ge_f32_e64 s[4:5], 0, v74
	v_add_u32_e32 v74, 1, v70
	s_nop 0
	v_cndmask_b32_e64 v72, v70, v72, s[4:5]
	v_fma_f32 v70, -v74, v70, v68
	v_cmp_lt_f32_e64 s[4:5], 0, v70
	s_nop 1
	v_cndmask_b32_e64 v70, v72, v74, s[4:5]
	v_mul_f32_e32 v72, 0x37800000, v70
	v_cndmask_b32_e32 v70, v70, v72, vcc
	v_cmp_class_f32_e32 vcc, v68, v250
	s_nop 1
	v_cndmask_b32_e32 v68, v70, v68, vcc
	v_div_scale_f32 v70, s[4:5], v68, v68, s20
	v_rcp_f32_e32 v72, v70
	s_nop 0
	v_fma_f32 v74, -v70, v72, 1.0
	v_fmac_f32_e32 v72, v74, v72
	v_div_scale_f32 v74, vcc, s20, v68, s20
	v_mul_f32_e32 v75, v74, v72
	v_fma_f32 v76, -v70, v75, v74
	v_fmac_f32_e32 v75, v76, v72
	v_fma_f32 v70, -v70, v75, v74
	v_div_fmas_f32 v70, v70, v72, v75
	v_div_fixup_f32 v68, v70, v68, s20
	v_cmp_gt_f32_e32 vcc, s19, v69
	v_mul_f32_e32 v70, 0x4f800000, v69
	s_nop 0
	v_cndmask_b32_e32 v69, v69, v70, vcc
	v_sqrt_f32_e32 v70, v69
	s_nop 0
	v_add_u32_e32 v72, -1, v70
	v_fma_f32 v74, -v72, v70, v69
	v_cmp_ge_f32_e64 s[4:5], 0, v74
	v_add_u32_e32 v74, 1, v70
	s_nop 0
	v_cndmask_b32_e64 v72, v70, v72, s[4:5]
	v_fma_f32 v70, -v74, v70, v69
	v_cmp_lt_f32_e64 s[4:5], 0, v70
	s_nop 1
	v_cndmask_b32_e64 v70, v72, v74, s[4:5]
	v_mul_f32_e32 v72, 0x37800000, v70
	v_cndmask_b32_e32 v70, v70, v72, vcc
	v_cmp_class_f32_e32 vcc, v69, v250
	s_nop 1
	v_cndmask_b32_e32 v69, v70, v69, vcc
	v_div_scale_f32 v70, s[4:5], v69, v69, s20
	v_rcp_f32_e32 v72, v70
	s_nop 0
	v_fma_f32 v74, -v70, v72, 1.0
	v_fmac_f32_e32 v72, v74, v72
	v_div_scale_f32 v74, vcc, s20, v69, s20
	v_mul_f32_e32 v75, v74, v72
	v_fma_f32 v76, -v70, v75, v74
	v_fmac_f32_e32 v75, v76, v72
	v_fma_f32 v70, -v70, v75, v74
	v_div_fmas_f32 v70, v70, v72, v75
	v_div_fixup_f32 v70, v70, v69, s20
	v_fmamk_f32 v69, v71, 0x3baaaaab, v245
	v_cmp_gt_f32_e32 vcc, s19, v69
	v_mul_f32_e32 v71, 0x4f800000, v69
	s_nop 0
	v_cndmask_b32_e32 v69, v69, v71, vcc
	v_sqrt_f32_e32 v71, v69
	s_nop 0
	v_add_u32_e32 v72, -1, v71
	v_fma_f32 v74, -v72, v71, v69
	v_cmp_ge_f32_e64 s[4:5], 0, v74
	v_add_u32_e32 v74, 1, v71
	s_nop 0
	v_cndmask_b32_e64 v72, v71, v72, s[4:5]
	v_fma_f32 v71, -v74, v71, v69
	v_cmp_lt_f32_e64 s[4:5], 0, v71
	s_nop 1
	v_cndmask_b32_e64 v71, v72, v74, s[4:5]
	v_mul_f32_e32 v72, 0x37800000, v71
	v_cndmask_b32_e32 v71, v71, v72, vcc
	v_cmp_class_f32_e32 vcc, v69, v250
	s_nop 1
	v_cndmask_b32_e32 v69, v71, v69, vcc
	v_div_scale_f32 v71, s[4:5], v69, v69, s20
	v_rcp_f32_e32 v72, v71
	s_nop 0
	v_fma_f32 v74, -v71, v72, 1.0
	v_fmac_f32_e32 v72, v74, v72
	v_div_scale_f32 v74, vcc, s20, v69, s20
	v_mul_f32_e32 v75, v74, v72
	v_fma_f32 v76, -v71, v75, v74
	v_fmac_f32_e32 v75, v76, v72
	v_fma_f32 v71, -v71, v75, v74
	v_div_fmas_f32 v71, v71, v72, v75
	v_div_fixup_f32 v72, v71, v69, s20
	v_fmamk_f32 v69, v73, 0x3baaaaab, v245
	v_cmp_gt_f32_e32 vcc, s19, v69
	v_mul_f32_e32 v71, 0x4f800000, v69
	s_nop 0
	v_cndmask_b32_e32 v69, v69, v71, vcc
	v_sqrt_f32_e32 v71, v69
	s_nop 0
	v_add_u32_e32 v73, -1, v71
	v_fma_f32 v74, -v73, v71, v69
	v_cmp_ge_f32_e64 s[4:5], 0, v74
	v_add_u32_e32 v74, 1, v71
	s_nop 0
	v_cndmask_b32_e64 v73, v71, v73, s[4:5]
	v_fma_f32 v71, -v74, v71, v69
	v_cmp_lt_f32_e64 s[4:5], 0, v71
	s_nop 1
	v_cndmask_b32_e64 v71, v73, v74, s[4:5]
	v_mul_f32_e32 v73, 0x37800000, v71
	v_cndmask_b32_e32 v71, v71, v73, vcc
	v_cmp_class_f32_e32 vcc, v69, v250
	s_nop 1
	v_cndmask_b32_e32 v69, v71, v69, vcc
	v_div_scale_f32 v71, s[4:5], v69, v69, s20
	v_rcp_f32_e32 v73, v71
	s_nop 0
	v_fma_f32 v74, -v71, v73, 1.0
	v_fmac_f32_e32 v73, v74, v73
	v_div_scale_f32 v74, vcc, s20, v69, s20
	v_mul_f32_e32 v75, v74, v73
	v_fma_f32 v76, -v71, v75, v74
	v_fmac_f32_e32 v75, v76, v73
	v_fma_f32 v71, -v71, v75, v74
	v_div_fmas_f32 v71, v71, v73, v75
	v_div_fixup_f32 v74, v71, v69, s20
	v_add_u32_e32 v69, 0x800, v193
	v_and_b32_e32 v71, 0x7cf0, v69
	v_add_u32_e32 v69, 0x80, v176
	s_and_saveexec_b64 s[4:5], s[0:1]
	s_cbranch_execz .LBB0_650
	v_add_u32_e32 v73, v195, v177
	s_movk_i32 s0, 0x60
	v_mul_lo_u32 v73, v73, s0
	v_sub_u32_e32 v73, v178, v73
	v_cmp_lt_i32_e32 vcc, 63, v73
	s_and_b64 vcc, s[42:43], vcc
	s_and_saveexec_b64 s[0:1], vcc
	s_cbranch_execz .LBB0_649
	v_subrev_u32_e32 v64, 64, v73
	v_lshrrev_b32_e32 v184, 1, v64
	v_lshlrev_b64 v[64:65], 2, v[184:185]
	v_lshl_add_u64 v[66:67], s[8:9], 0, v[64:65]
	v_lshlrev_b32_e32 v184, 2, v71
	v_lshl_add_u64 v[64:65], s[10:11], 0, v[64:65]
	v_lshl_add_u64 v[66:67], v[66:67], 0, v[184:185]
	v_lshl_add_u64 v[76:77], v[64:65], 0, v[184:185]
	global_load_dwordx4 v[152:155], v[66:67], off
	global_load_dwordx4 v[144:147], v[66:67], off offset:1024
	global_load_dwordx4 v[156:159], v[76:77], off
	global_load_dwordx4 v[148:151], v[76:77], off offset:1024
	global_load_dwordx4 v[132:135], v[66:67], off offset:2048
	s_nop 0
	global_load_dwordx4 v[64:67], v[66:67], off offset:3072
	s_nop 0
	global_load_dwordx4 v[136:139], v[76:77], off offset:2048
	global_load_dwordx4 v[140:143], v[76:77], off offset:3072

.LBB0_673:
	v_mov_b32_e32 v138, v185
	s_lshl_b32 s2, s47, 8
	v_mbcnt_lo_u32_b32 v138, -1, v138
	v_readlane_b32 s3, v253, 63
	v_mbcnt_hi_u32_b32 v138, -1, v138
	s_add_i32 s2, s2, s3
	v_and_or_b32 v140, v138, 15, s2
	s_cmp_eq_u32 s46, 0
	s_mov_b32 s2, 0x18900000
	s_cselect_b32 s2, s2, 0x19b00000
	v_ashrrev_i32_e32 v138, 1, v138
	s_add_u32 s36, s6, s2
	v_ashrrev_i32_e32 v141, 31, v140
	v_and_b32_e32 v138, -8, v138
	v_readlane_b32 s2, v254, 1
	s_mov_b32 s15, 0xf800000
	s_addc_u32 s37, s7, 0
	v_add_u32_e32 v142, s2, v138
	v_lshlrev_b64 v[138:139], 2, v[140:141]
	v_lshl_add_u64 v[148:149], s[12:13], 0, v[138:139]
	global_load_dword v143, v[148:149], off
	global_load_dword v146, v[148:149], off offset:64
	global_load_dword v150, v[148:149], off offset:128
	global_load_dword v220, v[148:149], off offset:512
	global_load_dword v221, v[148:149], off offset:576
	global_load_dword v222, v[148:149], off offset:640
	global_load_dword v223, v[148:149], off offset:704
	s_nop 0
	global_load_dword v149, v[148:149], off offset:192
	s_waitcnt vmcnt(0)
	v_fmamk_f32 v143, v143, 0x3c000000, v245
	v_cmp_gt_f32_e32 vcc, s15, v143
	v_mul_f32_e32 v144, 0x4f800000, v143
	s_nop 0
	v_cndmask_b32_e32 v143, v143, v144, vcc
	v_sqrt_f32_e32 v144, v143
	s_nop 0
	v_add_u32_e32 v148, -1, v144
	v_fma_f32 v151, -v148, v144, v143
	v_cmp_ge_f32_e64 s[2:3], 0, v151
	v_add_u32_e32 v151, 1, v144
	s_nop 0
	v_cndmask_b32_e64 v148, v144, v148, s[2:3]
	v_fma_f32 v144, -v151, v144, v143
	v_cmp_lt_f32_e64 s[2:3], 0, v144
	s_nop 1
	v_cndmask_b32_e64 v144, v148, v151, s[2:3]
	v_mul_f32_e32 v148, 0x37800000, v144
	v_cndmask_b32_e32 v144, v144, v148, vcc
	v_cmp_class_f32_e32 vcc, v143, v250
	s_nop 1
	v_cndmask_b32_e32 v143, v144, v143, vcc
	v_div_scale_f32 v144, s[2:3], v143, v143, 1.0
	v_rcp_f32_e32 v148, v144
	s_nop 0
	v_fma_f32 v151, -v144, v148, 1.0
	v_fmac_f32_e32 v148, v151, v148
	v_div_scale_f32 v151, vcc, 1.0, v143, 1.0
	v_mul_f32_e32 v152, v151, v148
	v_fma_f32 v153, -v144, v152, v151
	v_fmac_f32_e32 v152, v153, v148
	v_fma_f32 v144, -v144, v152, v151
	v_div_fmas_f32 v144, v144, v148, v152
	v_div_fixup_f32 v144, v144, v143, 1.0
	v_fmamk_f32 v143, v146, 0x3c000000, v245
	v_cmp_gt_f32_e32 vcc, s15, v143
	v_mul_f32_e32 v146, 0x4f800000, v143
	v_pk_mul_f32 v[126:127], v[126:127], v[144:145] op_sel_hi:[1,0]
	v_cndmask_b32_e32 v143, v143, v146, vcc
	v_sqrt_f32_e32 v146, v143
	v_pk_mul_f32 v[124:125], v[124:125], v[144:145] op_sel_hi:[1,0]
	v_pk_mul_f32 v[154:155], v[122:123], v[144:145] op_sel_hi:[1,0]
	v_pk_mul_f32 v[120:121], v[120:121], v[144:145] op_sel_hi:[1,0]
	v_add_u32_e32 v148, -1, v146
	v_fma_f32 v151, -v148, v146, v143
	v_cmp_ge_f32_e64 s[2:3], 0, v151
	v_add_u32_e32 v151, 1, v146
	v_cvt_pk_bf16_f32 v123, v126, v127
	v_cndmask_b32_e64 v148, v146, v148, s[2:3]
	v_fma_f32 v146, -v151, v146, v143
	v_cmp_lt_f32_e64 s[2:3], 0, v146
	v_cvt_pk_bf16_f32 v122, v124, v125
	v_cvt_pk_bf16_f32 v124, v120, v121
	v_cndmask_b32_e64 v146, v148, v151, s[2:3]
	v_mul_f32_e32 v148, 0x37800000, v146
	v_cndmask_b32_e32 v146, v146, v148, vcc
	v_cmp_class_f32_e32 vcc, v143, v250
	v_cvt_pk_bf16_f32 v125, v154, v155
	v_pk_mul_f32 v[118:119], v[118:119], v[144:145] op_sel_hi:[1,0]
	v_cndmask_b32_e32 v143, v146, v143, vcc
	v_div_scale_f32 v146, s[2:3], v143, v143, 1.0
	v_rcp_f32_e32 v148, v146
	v_pk_mul_f32 v[116:117], v[116:117], v[144:145] op_sel_hi:[1,0]
	v_fma_f32 v151, -v146, v148, 1.0
	v_fmac_f32_e32 v148, v151, v148
	v_div_scale_f32 v151, vcc, 1.0, v143, 1.0
	v_mul_f32_e32 v152, v151, v148
	v_fma_f32 v153, -v146, v152, v151
	v_fmac_f32_e32 v152, v153, v148
	v_fma_f32 v146, -v146, v152, v151
	v_div_fmas_f32 v146, v146, v148, v152
	v_div_fixup_f32 v146, v146, v143, 1.0
	v_fmamk_f32 v143, v150, 0x3c000000, v245
	v_cmp_gt_f32_e32 vcc, s15, v143
	v_mul_f32_e32 v148, 0x4f800000, v143
	v_pk_mul_f32 v[110:111], v[110:111], v[146:147] op_sel_hi:[1,0]
	v_cndmask_b32_e32 v143, v143, v148, vcc
	v_sqrt_f32_e32 v148, v143
	v_pk_mul_f32 v[108:109], v[108:109], v[146:147] op_sel_hi:[1,0]
	v_pk_mul_f32 v[102:103], v[102:103], v[146:147] op_sel_hi:[1,0]
	v_pk_mul_f32 v[100:101], v[100:101], v[146:147] op_sel_hi:[1,0]
	v_add_u32_e32 v150, -1, v148
	v_fma_f32 v151, -v150, v148, v143
	v_cmp_ge_f32_e64 s[2:3], 0, v151
	v_add_u32_e32 v151, 1, v148
	s_nop 0
	v_cndmask_b32_e64 v150, v148, v150, s[2:3]
	v_fma_f32 v148, -v151, v148, v143
	v_cmp_lt_f32_e64 s[2:3], 0, v148
	s_nop 1
	v_cndmask_b32_e64 v148, v150, v151, s[2:3]
	v_mul_f32_e32 v150, 0x37800000, v148
	v_cndmask_b32_e32 v148, v148, v150, vcc
	v_cmp_class_f32_e32 vcc, v143, v250
	s_nop 1
	v_cndmask_b32_e32 v143, v148, v143, vcc
	v_div_scale_f32 v148, s[2:3], v143, v143, 1.0
	v_rcp_f32_e32 v150, v148
	s_nop 0
	v_fma_f32 v151, -v148, v150, 1.0
	v_fmac_f32_e32 v150, v151, v150
	v_div_scale_f32 v151, vcc, 1.0, v143, 1.0
	v_mul_f32_e32 v152, v151, v150
	v_fma_f32 v153, -v148, v152, v151
	v_fmac_f32_e32 v152, v153, v150
	v_fma_f32 v148, -v148, v152, v151
	v_div_fmas_f32 v148, v148, v150, v152
	v_div_fixup_f32 v148, v148, v143, 1.0
	v_fmamk_f32 v143, v149, 0x3c000000, v245
	v_cmp_gt_f32_e32 vcc, s15, v143
	v_mul_f32_e32 v149, 0x4f800000, v143
	s_nop 0
	v_cndmask_b32_e32 v143, v143, v149, vcc
	v_sqrt_f32_e32 v149, v143
	s_nop 0
	v_add_u32_e32 v150, -1, v149
	v_fma_f32 v151, -v150, v149, v143
	v_cmp_ge_f32_e64 s[2:3], 0, v151
	v_add_u32_e32 v151, 1, v149
	s_nop 0
	v_cndmask_b32_e64 v150, v149, v150, s[2:3]
	v_fma_f32 v149, -v151, v149, v143
	v_cmp_lt_f32_e64 s[2:3], 0, v149
	s_nop 1
	v_cndmask_b32_e64 v149, v150, v151, s[2:3]
	v_mul_f32_e32 v150, 0x37800000, v149
	v_cndmask_b32_e32 v149, v149, v150, vcc
	v_cmp_class_f32_e32 vcc, v143, v250
	s_nop 1
	v_cndmask_b32_e32 v143, v149, v143, vcc
	v_div_scale_f32 v149, s[2:3], v143, v143, 1.0
	v_rcp_f32_e32 v150, v149
	s_mov_b32 s2, 0x24000
	v_fma_f32 v151, -v149, v150, 1.0
	v_fmac_f32_e32 v150, v151, v150
	v_div_scale_f32 v151, vcc, 1.0, v143, 1.0
	v_mul_f32_e32 v152, v151, v150
	v_fma_f32 v153, -v149, v152, v151
	v_fmac_f32_e32 v152, v153, v150
	v_fma_f32 v149, -v149, v152, v151
	v_div_fmas_f32 v149, v149, v150, v152
	v_div_fixup_f32 v150, v149, v143, 1.0
	v_lshlrev_b64 v[152:153], 9, v[140:141]
	v_ashrrev_i32_e32 v143, 31, v142
	v_lshl_add_u64 v[152:153], s[36:37], 0, v[152:153]
	v_lshlrev_b64 v[126:127], 1, v[142:143]
	v_lshl_add_u64 v[120:121], v[152:153], 0, v[126:127]
	global_store_dwordx4 v[120:121], v[122:125], off
	v_pk_mul_f32 v[94:95], v[94:95], v[148:149] op_sel_hi:[1,0]
	v_pk_mul_f32 v[92:93], v[92:93], v[148:149] op_sel_hi:[1,0]
	v_pk_mul_f32 v[122:123], v[114:115], v[144:145] op_sel_hi:[1,0]
	v_pk_mul_f32 v[114:115], v[112:113], v[144:145] op_sel_hi:[1,0]
	v_cvt_pk_bf16_f32 v112, v116, v117
	v_cvt_pk_bf16_f32 v113, v118, v119
	v_cvt_pk_bf16_f32 v114, v114, v115
	v_cvt_pk_bf16_f32 v115, v122, v123
	global_store_dwordx4 v[120:121], v[112:115], off offset:256
	v_pk_mul_f32 v[86:87], v[86:87], v[148:149] op_sel_hi:[1,0]
	v_pk_mul_f32 v[84:85], v[84:85], v[148:149] op_sel_hi:[1,0]
	v_or_b32_e32 v112, 16, v140
	v_ashrrev_i32_e32 v113, 31, v112
	v_lshlrev_b64 v[112:113], 9, v[112:113]
	v_lshl_add_u64 v[112:113], s[36:37], 0, v[112:113]
	v_pk_mul_f32 v[114:115], v[106:107], v[146:147] op_sel_hi:[1,0]
	v_pk_mul_f32 v[106:107], v[104:105], v[146:147] op_sel_hi:[1,0]
	v_cvt_pk_bf16_f32 v104, v108, v109
	v_cvt_pk_bf16_f32 v105, v110, v111
	v_cvt_pk_bf16_f32 v106, v106, v107
	v_cvt_pk_bf16_f32 v107, v114, v115
	v_lshl_add_u64 v[108:109], v[112:113], 0, v[126:127]
	global_store_dwordx4 v[108:109], v[104:107], off
	v_pk_mul_f32 v[78:79], v[78:79], v[150:151] op_sel_hi:[1,0]
	v_pk_mul_f32 v[76:77], v[76:77], v[150:151] op_sel_hi:[1,0]
	v_pk_mul_f32 v[104:105], v[98:99], v[146:147] op_sel_hi:[1,0]
	v_pk_mul_f32 v[98:99], v[96:97], v[146:147] op_sel_hi:[1,0]
	v_cvt_pk_bf16_f32 v96, v100, v101
	v_cvt_pk_bf16_f32 v97, v102, v103
	v_cvt_pk_bf16_f32 v98, v98, v99
	v_cvt_pk_bf16_f32 v99, v104, v105
	global_store_dwordx4 v[108:109], v[96:99], off offset:256
	v_pk_mul_f32 v[70:71], v[70:71], v[150:151] op_sel_hi:[1,0]
	v_pk_mul_f32 v[68:69], v[68:69], v[150:151] op_sel_hi:[1,0]
	v_or_b32_e32 v96, 32, v140
	v_ashrrev_i32_e32 v97, 31, v96
	v_lshlrev_b64 v[96:97], 9, v[96:97]
	v_lshl_add_u64 v[96:97], s[36:37], 0, v[96:97]
	v_pk_mul_f32 v[98:99], v[90:91], v[148:149] op_sel_hi:[1,0]
	v_pk_mul_f32 v[90:91], v[88:89], v[148:149] op_sel_hi:[1,0]
	v_cvt_pk_bf16_f32 v88, v92, v93
	v_cvt_pk_bf16_f32 v89, v94, v95
	v_cvt_pk_bf16_f32 v90, v90, v91
	v_cvt_pk_bf16_f32 v91, v98, v99
	v_lshl_add_u64 v[92:93], v[96:97], 0, v[126:127]
	global_store_dwordx4 v[92:93], v[88:91], off
	s_nop 1
	v_pk_mul_f32 v[88:89], v[82:83], v[148:149] op_sel_hi:[1,0]
	v_pk_mul_f32 v[82:83], v[80:81], v[148:149] op_sel_hi:[1,0]
	v_cvt_pk_bf16_f32 v80, v84, v85
	v_cvt_pk_bf16_f32 v81, v86, v87
	v_cvt_pk_bf16_f32 v82, v82, v83
	v_cvt_pk_bf16_f32 v83, v88, v89
	global_store_dwordx4 v[92:93], v[80:83], off offset:256
	s_nop 1
	v_or_b32_e32 v80, 48, v140
	v_ashrrev_i32_e32 v81, 31, v80
	v_lshlrev_b64 v[80:81], 9, v[80:81]
	v_lshl_add_u64 v[80:81], s[36:37], 0, v[80:81]
	v_pk_mul_f32 v[82:83], v[74:75], v[150:151] op_sel_hi:[1,0]
	v_pk_mul_f32 v[74:75], v[72:73], v[150:151] op_sel_hi:[1,0]
	v_cvt_pk_bf16_f32 v72, v76, v77
	v_cvt_pk_bf16_f32 v73, v78, v79
	v_cvt_pk_bf16_f32 v74, v74, v75
	v_cvt_pk_bf16_f32 v75, v82, v83
	v_lshl_add_u64 v[76:77], v[80:81], 0, v[126:127]
	global_store_dwordx4 v[76:77], v[72:75], off
	s_nop 1
	v_pk_mul_f32 v[72:73], v[66:67], v[150:151] op_sel_hi:[1,0]
	v_pk_mul_f32 v[66:67], v[64:65], v[150:151] op_sel_hi:[1,0]
	v_cvt_pk_bf16_f32 v64, v68, v69
	v_cvt_pk_bf16_f32 v65, v70, v71
	v_cvt_pk_bf16_f32 v66, v66, v67
	v_cvt_pk_bf16_f32 v67, v72, v73
	global_store_dwordx4 v[76:77], v[64:67], off offset:256
	s_nop 1
	v_lshl_add_u64 v[64:65], s[8:9], 0, v[138:139]
	v_add_co_u32_e32 v64, vcc, s2, v64
	s_nop 1
	v_addc_co_u32_e32 v65, vcc, 0, v65, vcc
	s_nop 1
	v_mov_b32_e32 v66, v220
	v_mov_b32_e32 v67, v221
	v_mov_b32_e32 v68, v222
	v_mov_b32_e32 v65, v223
	v_fmamk_f32 v64, v66, 0x3c000000, v245
	v_cmp_gt_f32_e32 vcc, s15, v64
	v_mul_f32_e32 v66, 0x4f800000, v64
	v_fmamk_f32 v65, v65, 0x3c000000, v245
	v_cndmask_b32_e32 v64, v64, v66, vcc
	v_sqrt_f32_e32 v66, v64
	s_nop 0
	v_add_u32_e32 v69, -1, v66
	v_fma_f32 v70, -v69, v66, v64
	v_cmp_ge_f32_e64 s[2:3], 0, v70
	v_add_u32_e32 v70, 1, v66
	s_nop 0
	v_cndmask_b32_e64 v69, v66, v69, s[2:3]
	v_fma_f32 v66, -v70, v66, v64
	v_cmp_lt_f32_e64 s[2:3], 0, v66
	s_nop 1
	v_cndmask_b32_e64 v66, v69, v70, s[2:3]
	v_mul_f32_e32 v69, 0x37800000, v66
	v_cndmask_b32_e32 v66, v66, v69, vcc
	v_cmp_class_f32_e32 vcc, v64, v250
	s_nop 1
	v_cndmask_b32_e32 v64, v66, v64, vcc
	v_div_scale_f32 v66, s[2:3], v64, v64, 1.0
	v_rcp_f32_e32 v69, v66
	s_nop 0
	v_fma_f32 v70, -v66, v69, 1.0
	v_fmac_f32_e32 v69, v70, v69
	v_div_scale_f32 v70, vcc, 1.0, v64, 1.0
	v_mul_f32_e32 v71, v70, v69
	v_fma_f32 v72, -v66, v71, v70
	v_fmac_f32_e32 v71, v72, v69
	v_fma_f32 v66, -v66, v71, v70
	v_div_fmas_f32 v66, v66, v69, v71
	v_div_fixup_f32 v64, v66, v64, 1.0
	v_fmamk_f32 v66, v67, 0x3c000000, v245
	v_cmp_gt_f32_e32 vcc, s15, v66
	v_mul_f32_e32 v67, 0x4f800000, v66
	s_nop 0
	v_cndmask_b32_e32 v66, v66, v67, vcc
	v_sqrt_f32_e32 v67, v66
	s_nop 0
	v_add_u32_e32 v69, -1, v67
	v_fma_f32 v70, -v69, v67, v66
	v_cmp_ge_f32_e64 s[2:3], 0, v70
	v_add_u32_e32 v70, 1, v67
	s_nop 0
	v_cndmask_b32_e64 v69, v67, v69, s[2:3]
	v_fma_f32 v67, -v70, v67, v66
	v_cmp_lt_f32_e64 s[2:3], 0, v67
	s_nop 1
	v_cndmask_b32_e64 v67, v69, v70, s[2:3]
	v_mul_f32_e32 v69, 0x37800000, v67
	v_cndmask_b32_e32 v67, v67, v69, vcc
	v_cmp_class_f32_e32 vcc, v66, v250
	s_nop 1
	v_cndmask_b32_e32 v66, v67, v66, vcc
	v_div_scale_f32 v67, s[2:3], v66, v66, 1.0
	v_rcp_f32_e32 v69, v67
	s_nop 0
	v_fma_f32 v70, -v67, v69, 1.0
	v_fmac_f32_e32 v69, v70, v69
	v_div_scale_f32 v70, vcc, 1.0, v66, 1.0
	v_mul_f32_e32 v71, v70, v69
	v_fma_f32 v72, -v67, v71, v70
	v_fmac_f32_e32 v71, v72, v69
	v_fma_f32 v67, -v67, v71, v70
	v_div_fmas_f32 v67, v67, v69, v71
	v_div_fixup_f32 v66, v67, v66, 1.0
	v_fmamk_f32 v67, v68, 0x3c000000, v245
	v_cmp_gt_f32_e32 vcc, s15, v67
	v_mul_f32_e32 v68, 0x4f800000, v67
	s_nop 0
	v_cndmask_b32_e32 v67, v67, v68, vcc
	v_sqrt_f32_e32 v68, v67
	s_nop 0
	v_add_u32_e32 v69, -1, v68
	v_fma_f32 v70, -v69, v68, v67
	v_cmp_ge_f32_e64 s[2:3], 0, v70
	v_add_u32_e32 v70, 1, v68
	s_nop 0
	v_cndmask_b32_e64 v69, v68, v69, s[2:3]
	v_fma_f32 v68, -v70, v68, v67
	v_cmp_lt_f32_e64 s[2:3], 0, v68
	s_nop 1
	v_cndmask_b32_e64 v68, v69, v70, s[2:3]
	v_mul_f32_e32 v69, 0x37800000, v68
	v_cndmask_b32_e32 v68, v68, v69, vcc
	v_cmp_class_f32_e32 vcc, v67, v250
	s_nop 1
	v_cndmask_b32_e32 v67, v68, v67, vcc
	v_div_scale_f32 v68, s[2:3], v67, v67, 1.0
	v_rcp_f32_e32 v69, v68
	s_nop 0
	v_fma_f32 v70, -v68, v69, 1.0
	v_fmac_f32_e32 v69, v70, v69
	v_div_scale_f32 v70, vcc, 1.0, v67, 1.0
	v_mul_f32_e32 v71, v70, v69
	v_fma_f32 v72, -v68, v71, v70
	v_fmac_f32_e32 v71, v72, v69
	v_fma_f32 v68, -v68, v71, v70
	v_div_fmas_f32 v68, v68, v69, v71
	v_div_fixup_f32 v68, v68, v67, 1.0
	v_cmp_gt_f32_e32 vcc, s15, v65
	v_mul_f32_e32 v67, 0x4f800000, v65
	s_nop 0
	v_cndmask_b32_e32 v65, v65, v67, vcc
	v_sqrt_f32_e32 v67, v65
	s_nop 0
	v_add_u32_e32 v69, -1, v67
	v_fma_f32 v70, -v69, v67, v65
	v_cmp_ge_f32_e64 s[2:3], 0, v70
	v_add_u32_e32 v70, 1, v67
	s_nop 0
	v_cndmask_b32_e64 v69, v67, v69, s[2:3]
	v_fma_f32 v67, -v70, v67, v65
	v_cmp_lt_f32_e64 s[2:3], 0, v67
	s_nop 1
	v_cndmask_b32_e64 v67, v69, v70, s[2:3]
	v_mul_f32_e32 v69, 0x37800000, v67
	v_cndmask_b32_e32 v67, v67, v69, vcc
	v_cmp_class_f32_e32 vcc, v65, v250
	s_nop 1
	v_cndmask_b32_e32 v65, v67, v65, vcc
	v_div_scale_f32 v67, s[2:3], v65, v65, 1.0
	v_rcp_f32_e32 v69, v67
	v_pk_mul_f32 v[60:61], v[60:61], v[64:65] op_sel_hi:[1,0]
	s_mov_b64 s[2:3], 0x10000
	v_pk_mul_f32 v[62:63], v[62:63], v[64:65] op_sel_hi:[1,0]
	v_fma_f32 v70, -v67, v69, 1.0
	v_fmac_f32_e32 v69, v70, v69
	v_div_scale_f32 v70, vcc, 1.0, v65, 1.0
	v_mul_f32_e32 v71, v70, v69
	v_fma_f32 v72, -v67, v71, v70
	v_fmac_f32_e32 v71, v72, v69
	v_fma_f32 v67, -v67, v71, v70
	v_pk_mul_f32 v[72:73], v[58:59], v[64:65] op_sel_hi:[1,0]
	v_pk_mul_f32 v[58:59], v[56:57], v[64:65] op_sel_hi:[1,0]
	v_cvt_pk_bf16_f32 v56, v60, v61
	v_lshl_add_u64 v[60:61], v[120:121], 0, s[2:3]
	s_mov_b32 s2, 0x10000
	v_div_fmas_f32 v67, v67, v69, v71
	v_cvt_pk_bf16_f32 v57, v62, v63
	v_add_co_u32_e32 v62, vcc, s2, v120
	v_cvt_pk_bf16_f32 v58, v58, v59
	v_cvt_pk_bf16_f32 v59, v72, v73
	v_addc_co_u32_e32 v63, vcc, 0, v121, vcc
	global_store_dwordx4 v[62:63], v[56:59], off
	v_pk_mul_f32 v[54:55], v[54:55], v[64:65] op_sel_hi:[1,0]
	v_pk_mul_f32 v[52:53], v[52:53], v[64:65] op_sel_hi:[1,0]
	v_pk_mul_f32 v[56:57], v[50:51], v[64:65] op_sel_hi:[1,0]
	v_pk_mul_f32 v[50:51], v[48:49], v[64:65] op_sel_hi:[1,0]
	v_cvt_pk_bf16_f32 v48, v52, v53
	v_cvt_pk_bf16_f32 v49, v54, v55
	v_cvt_pk_bf16_f32 v50, v50, v51
	v_cvt_pk_bf16_f32 v51, v56, v57
	v_pk_mul_f32 v[44:45], v[44:45], v[66:67] op_sel_hi:[1,0]
	s_mov_b64 s[2:3], 0x12000
	global_store_dwordx4 v[60:61], v[48:51], off offset:256
	v_pk_mul_f32 v[46:47], v[46:47], v[66:67] op_sel_hi:[1,0]
	v_pk_mul_f32 v[38:39], v[38:39], v[66:67] op_sel_hi:[1,0]
	v_pk_mul_f32 v[48:49], v[42:43], v[66:67] op_sel_hi:[1,0]
	v_pk_mul_f32 v[42:43], v[40:41], v[66:67] op_sel_hi:[1,0]
	v_cvt_pk_bf16_f32 v40, v44, v45
	v_lshl_add_u64 v[44:45], v[120:121], 0, s[2:3]
	s_mov_b32 s2, 0x12000
	v_cvt_pk_bf16_f32 v41, v46, v47
	v_add_co_u32_e32 v46, vcc, s2, v120
	v_cvt_pk_bf16_f32 v42, v42, v43
	v_cvt_pk_bf16_f32 v43, v48, v49
	v_addc_co_u32_e32 v47, vcc, 0, v121, vcc
	global_store_dwordx4 v[46:47], v[40:43], off
	v_pk_mul_f32 v[36:37], v[36:37], v[66:67] op_sel_hi:[1,0]
	v_pk_mul_f32 v[28:29], v[28:29], v[68:69] op_sel_hi:[1,0]
	v_pk_mul_f32 v[40:41], v[34:35], v[66:67] op_sel_hi:[1,0]
	v_pk_mul_f32 v[34:35], v[32:33], v[66:67] op_sel_hi:[1,0]
	v_cvt_pk_bf16_f32 v32, v36, v37
	v_cvt_pk_bf16_f32 v33, v38, v39
	v_cvt_pk_bf16_f32 v34, v34, v35
	v_cvt_pk_bf16_f32 v35, v40, v41
	s_mov_b64 s[2:3], 0x14000
	global_store_dwordx4 v[44:45], v[32:35], off offset:256
	v_pk_mul_f32 v[30:31], v[30:31], v[68:69] op_sel_hi:[1,0]
	v_div_fixup_f32 v70, v67, v65, 1.0
	v_pk_mul_f32 v[32:33], v[26:27], v[68:69] op_sel_hi:[1,0]
	v_pk_mul_f32 v[26:27], v[24:25], v[68:69] op_sel_hi:[1,0]
	v_cvt_pk_bf16_f32 v24, v28, v29
	v_lshl_add_u64 v[28:29], v[120:121], 0, s[2:3]
	s_mov_b32 s2, 0x14000
	v_cvt_pk_bf16_f32 v25, v30, v31
	v_add_co_u32_e32 v30, vcc, s2, v120
	v_cvt_pk_bf16_f32 v26, v26, v27
	v_cvt_pk_bf16_f32 v27, v32, v33
	v_addc_co_u32_e32 v31, vcc, 0, v121, vcc
	global_store_dwordx4 v[30:31], v[24:27], off
	v_pk_mul_f32 v[22:23], v[22:23], v[68:69] op_sel_hi:[1,0]
	v_pk_mul_f32 v[20:21], v[20:21], v[68:69] op_sel_hi:[1,0]
	v_pk_mul_f32 v[24:25], v[18:19], v[68:69] op_sel_hi:[1,0]
	v_pk_mul_f32 v[18:19], v[16:17], v[68:69] op_sel_hi:[1,0]
	v_cvt_pk_bf16_f32 v16, v20, v21
	v_cvt_pk_bf16_f32 v17, v22, v23
	v_cvt_pk_bf16_f32 v18, v18, v19
	v_cvt_pk_bf16_f32 v19, v24, v25
	v_pk_mul_f32 v[12:13], v[12:13], v[70:71] op_sel_hi:[1,0]
	s_mov_b64 s[2:3], 0x16000
	global_store_dwordx4 v[28:29], v[16:19], off offset:256
	v_pk_mul_f32 v[14:15], v[14:15], v[70:71] op_sel_hi:[1,0]
	v_pk_mul_f32 v[6:7], v[6:7], v[70:71] op_sel_hi:[1,0]
	v_pk_mul_f32 v[16:17], v[10:11], v[70:71] op_sel_hi:[1,0]
	v_pk_mul_f32 v[10:11], v[8:9], v[70:71] op_sel_hi:[1,0]
	v_cvt_pk_bf16_f32 v8, v12, v13
	v_lshl_add_u64 v[12:13], v[120:121], 0, s[2:3]
	s_mov_b32 s2, 0x16000
	v_cvt_pk_bf16_f32 v9, v14, v15
	v_add_co_u32_e32 v14, vcc, s2, v120
	v_cvt_pk_bf16_f32 v10, v10, v11
	v_cvt_pk_bf16_f32 v11, v16, v17
	v_addc_co_u32_e32 v15, vcc, 0, v121, vcc
	global_store_dwordx4 v[14:15], v[8:11], off
	v_pk_mul_f32 v[4:5], v[4:5], v[70:71] op_sel_hi:[1,0]
	s_mov_b64 s[2:3], -1
	v_pk_mul_f32 v[8:9], v[2:3], v[70:71] op_sel_hi:[1,0]
	v_pk_mul_f32 v[2:3], v[0:1], v[70:71] op_sel_hi:[1,0]
	v_cvt_pk_bf16_f32 v0, v4, v5
	v_cvt_pk_bf16_f32 v1, v6, v7
	v_cvt_pk_bf16_f32 v2, v2, v3
	v_cvt_pk_bf16_f32 v3, v8, v9
	global_store_dwordx4 v[12:13], v[0:3], off offset:256
	s_and_b64 vcc, exec, s[0:1]
	s_cbranch_vccnz .LBB0_663
	s_and_b64 vcc, exec, s[4:5]
	s_cbranch_vccnz .LBB0_662
	s_barrier
	s_branch .LBB0_662
